# gather static priority raise for waves 4..7 combined with the 0/2/4/6 us de-phasing of the attention w_o GEMM
# speedup vs baseline: 1.0040x; 1.0008x over previous
.LBB0_850:
	s_cmp_lt_i32 s56, 13
	s_cselect_b64 s[0:1], -1, 0
	s_and_b64 s[8:9], s[0:1], s[4:5]
	s_andn2_b64 vcc, exec, s[8:9]
	s_cbranch_vccnz .LBB0_889
	s_bfe_u32 s97, s2, 0x20003
	s_cmp_eq_u32 s97, 0
	s_cbranch_scc1 .Lstag_WO_done
	s_mul_i32 s97, s97, 1
.Lstag_WO:
	s_add_i32 s97, s97, -1
	s_cmp_eq_u32 s97, 0
	s_sleep 63
	s_cbranch_scc0 .Lstag_WO
